# epilogue de-serialisation: MLA gated-store ladder prefetches all 16 gate loads, counted vmcnt(15) instead of vmcnt(0) per store
# speedup vs baseline: 1.0159x; 1.0009x over previous
; DI unsigned pk2(float a, float b) { f32v2 f = {a, b}; bf16v2 r = __builtin_convertvector(f, bf16v2); return __builtin_bit_cast(unsigned, r); }
; DI float bflo(unsigned w) { return __uint_as_float(w << 16); }
; DI float bfhi(unsigned w) { return __uint_as_float(w & 0xffff0000u); }
; template <int DQK, int MODE, bool PIPE>
; DI void attn_core(const u16* __restrict__ Qg, const u16* __restrict__ Kg, const u16* __restrict__ Vtg, int ntiles,
;                   int kr_lo, int rs, int r_q, int c_q, int cs, const float* biasL, char* lds, f32x16 (&o)[4], float& l_out, int tid) {
;     ...
;   l_out = l + __shfl_xor(l, 32);
; }
; DI void store_gated(const Params& p, int R, int colbase, f32x16 (&o)[4], float mult, const float* wv, int h) {
; #pragma unroll
;   for (int d0 = 0; d0 < 4; ++d0)
; #pragma unroll
;     for (int g = 0; g < 4; ++g) {
;       const int dv = 32 * d0 + 8 * g + 4 * h;
;       const size_t off = (size_t)R * DM + colbase + dv;
;       const u32x2 gg = *(const u32x2*)(p.Gs + off);
;       float v0 = o[d0][4 * g] * mult, v1 = o[d0][4 * g + 1] * mult, v2 = o[d0][4 * g + 2] * mult, v3 = o[d0][4 * g + 3] * mult;
;       if (wv) { v0 *= wv[dv]; v1 *= wv[dv + 1]; v2 *= wv[dv + 2]; v3 *= wv[dv + 3]; }
;       u32x2 ov = {pk2(v0 * bflo(gg[0]), v1 * bfhi(gg[0])), pk2(v2 * bflo(gg[1]), v3 * bfhi(gg[1]))};
;       *(u32x2*)(p.H + off) = ov;
;       __builtin_amdgcn_sched_barrier(0);
;     }
; }
;     ...
;       const int j = it - N_DIFF, hd = j / 65, qb = j % 65, q0 = qb * 256, nt = qb == 0 ? 4 : NR / 64;
;       attn_core<192, 0, false>(p.Qmla + ((size_t)hd * NR + q0) * 192, p.Kmla + (size_t)hd * NR * 192, p.VtMla + (size_t)hd * 128 * NR, nt, 0, 0, 0, 0, 0, biasL, lds, o, l, tid);
;       store_gated(p, q0 + wid * 32 + r32, hd * 128, o, 1.f / l, nullptr, h);
.LBB0_831:
	s_and_b32 s0, 0xffff, s16
	v_lshl_add_u32 v0, v197, 5, s0
	v_or_b32_e32 v66, v0, v193
	v_ashrrev_i32_e32 v67, 31, v66
	s_lshl_b32 s12, s12, 7
	v_lshlrev_b64 v[66:67], 11, v[66:67]
	v_lshl_add_u64 v[66:67], v[66:67], 0, s[12:13]
	v_lshl_or_b32 v66, v195, 2, v66
	v_readlane_b32 s8, v252, 2
	v_lshlrev_b64 v[68:69], 1, v[66:67]
	v_readlane_b32 s10, v252, 4
	v_readlane_b32 s11, v252, 5
	v_and_b32_e32 v72, 64, v189
	v_xor_b32_e32 v0, 32, v189
	v_lshl_add_u64 v[66:67], s[10:11], 0, v[68:69]
	global_load_dwordx2 v[98:99], v[66:67], off
	global_load_dwordx2 v[100:101], v[66:67], off offset:16
	global_load_dwordx2 v[102:103], v[66:67], off offset:32
	global_load_dwordx2 v[104:105], v[66:67], off offset:48
	global_load_dwordx2 v[106:107], v[66:67], off offset:64
	global_load_dwordx2 v[108:109], v[66:67], off offset:80
	global_load_dwordx2 v[110:111], v[66:67], off offset:96
	global_load_dwordx2 v[112:113], v[66:67], off offset:112
	global_load_dwordx2 v[114:115], v[66:67], off offset:128
	global_load_dwordx2 v[116:117], v[66:67], off offset:144
	global_load_dwordx2 v[118:119], v[66:67], off offset:160
	global_load_dwordx2 v[120:121], v[66:67], off offset:176
	global_load_dwordx2 v[122:123], v[66:67], off offset:192
	global_load_dwordx2 v[124:125], v[66:67], off offset:208
	global_load_dwordx2 v[126:127], v[66:67], off offset:224
	global_load_dwordx2 v[128:129], v[66:67], off offset:240
	v_add_u32_e32 v72, 64, v72
	v_cmp_lt_i32_e32 vcc, v0, v72
	v_readlane_b32 s9, v252, 3
	s_nop 0
	v_cndmask_b32_e32 v0, v189, v0, vcc
	v_lshlrev_b32_e32 v0, 2, v0
	ds_bpermute_b32 v0, v0, v222
	s_waitcnt lgkmcnt(0)
	v_add_f32_e32 v0, v222, v0
	v_div_scale_f32 v72, s[0:1], v0, v0, 1.0
	v_rcp_f32_e32 v73, v72
	v_div_scale_f32 v74, vcc, 1.0, v0, 1.0
	v_fma_f32 v75, -v72, v73, 1.0
	v_fmac_f32_e32 v73, v75, v73
	v_mul_f32_e32 v75, v74, v73
	v_fma_f32 v76, -v72, v75, v74
	v_fmac_f32_e32 v75, v76, v73
	v_fma_f32 v72, -v72, v75, v74
	v_div_fmas_f32 v72, v72, v73, v75
	v_div_fixup_f32 v0, v72, v0, 1.0
	v_pk_mul_f32 v[50:51], v[50:51], v[0:1] op_sel_hi:[1,0]
	v_pk_mul_f32 v[52:53], v[52:53], v[0:1] op_sel_hi:[1,0]
	s_waitcnt vmcnt(15)
	v_mov_b32_e32 v70, v98
	v_mov_b32_e32 v71, v99
	v_lshlrev_b32_e32 v72, 16, v70
	v_and_b32_e32 v73, 0xffff0000, v70
	v_lshlrev_b32_e32 v70, 16, v71
	v_and_b32_e32 v71, 0xffff0000, v71
	v_pk_mul_f32 v[50:51], v[50:51], v[72:73]
	v_pk_mul_f32 v[52:53], v[52:53], v[70:71]
	v_cvt_pk_bf16_f32 v70, v50, v51
	v_cvt_pk_bf16_f32 v71, v52, v53
	v_lshl_add_u64 v[50:51], s[74:75], 0, v[68:69]
	global_store_dwordx2 v[50:51], v[70:71], off
	v_pk_mul_f32 v[54:55], v[54:55], v[0:1] op_sel_hi:[1,0]
	s_waitcnt vmcnt(15)
	v_mov_b32_e32 v52, v100
	v_mov_b32_e32 v53, v101
	v_lshlrev_b32_e32 v68, 16, v52
	v_and_b32_e32 v69, 0xffff0000, v52
	v_pk_mul_f32 v[54:55], v[54:55], v[68:69]
	s_nop 0
	v_cvt_pk_bf16_f32 v52, v54, v55
	v_pk_mul_f32 v[54:55], v[56:57], v[0:1] op_sel_hi:[1,0]
	v_lshlrev_b32_e32 v56, 16, v53
	v_and_b32_e32 v57, 0xffff0000, v53
	v_pk_mul_f32 v[54:55], v[54:55], v[56:57]
	s_nop 0
	v_cvt_pk_bf16_f32 v53, v54, v55
	global_store_dwordx2 v[50:51], v[52:53], off offset:16
	v_pk_mul_f32 v[54:55], v[58:59], v[0:1] op_sel_hi:[1,0]
	s_waitcnt vmcnt(15)
	v_mov_b32_e32 v52, v102
	v_mov_b32_e32 v53, v103
	v_lshlrev_b32_e32 v56, 16, v52
	v_and_b32_e32 v57, 0xffff0000, v52
	v_pk_mul_f32 v[54:55], v[54:55], v[56:57]
	v_lshlrev_b32_e32 v56, 16, v53
	v_cvt_pk_bf16_f32 v52, v54, v55
	v_pk_mul_f32 v[54:55], v[60:61], v[0:1] op_sel_hi:[1,0]
	v_and_b32_e32 v57, 0xffff0000, v53
	v_pk_mul_f32 v[54:55], v[54:55], v[56:57]
	s_nop 0
	v_cvt_pk_bf16_f32 v53, v54, v55
	global_store_dwordx2 v[50:51], v[52:53], off offset:32
	v_pk_mul_f32 v[54:55], v[62:63], v[0:1] op_sel_hi:[1,0]
	v_pk_mul_f32 v[56:57], v[64:65], v[0:1] op_sel_hi:[1,0]
	s_waitcnt vmcnt(15)
	v_mov_b32_e32 v52, v104
	v_mov_b32_e32 v53, v105
	v_lshlrev_b32_e32 v58, 16, v52
	v_and_b32_e32 v59, 0xffff0000, v52
	v_lshlrev_b32_e32 v52, 16, v53
	v_and_b32_e32 v53, 0xffff0000, v53
	v_pk_mul_f32 v[54:55], v[54:55], v[58:59]
	v_pk_mul_f32 v[52:53], v[56:57], v[52:53]
	v_cvt_pk_bf16_f32 v54, v54, v55
	v_cvt_pk_bf16_f32 v55, v52, v53
	global_store_dwordx2 v[50:51], v[54:55], off offset:48
	v_pk_mul_f32 v[34:35], v[34:35], v[0:1] op_sel_hi:[1,0]
	v_pk_mul_f32 v[36:37], v[36:37], v[0:1] op_sel_hi:[1,0]
	s_waitcnt vmcnt(15)
	v_mov_b32_e32 v52, v106
	v_mov_b32_e32 v53, v107
	v_lshlrev_b32_e32 v54, 16, v52
	v_and_b32_e32 v55, 0xffff0000, v52
	v_lshlrev_b32_e32 v52, 16, v53
	v_and_b32_e32 v53, 0xffff0000, v53
	v_pk_mul_f32 v[34:35], v[34:35], v[54:55]
	v_pk_mul_f32 v[36:37], v[36:37], v[52:53]
	v_cvt_pk_bf16_f32 v34, v34, v35
	v_cvt_pk_bf16_f32 v35, v36, v37
	global_store_dwordx2 v[50:51], v[34:35], off offset:64
	v_pk_mul_f32 v[36:37], v[38:39], v[0:1] op_sel_hi:[1,0]
	s_waitcnt vmcnt(15)
	v_mov_b32_e32 v34, v108
	v_mov_b32_e32 v35, v109
	v_lshlrev_b32_e32 v38, 16, v34
	v_and_b32_e32 v39, 0xffff0000, v34
	v_pk_mul_f32 v[36:37], v[36:37], v[38:39]
	v_lshlrev_b32_e32 v38, 16, v35
	v_cvt_pk_bf16_f32 v34, v36, v37
	v_pk_mul_f32 v[36:37], v[40:41], v[0:1] op_sel_hi:[1,0]
	v_and_b32_e32 v39, 0xffff0000, v35
	v_pk_mul_f32 v[36:37], v[36:37], v[38:39]
	s_nop 0
	v_cvt_pk_bf16_f32 v35, v36, v37
	global_store_dwordx2 v[50:51], v[34:35], off offset:80
	v_pk_mul_f32 v[36:37], v[42:43], v[0:1] op_sel_hi:[1,0]
	s_waitcnt vmcnt(15)
; DI unsigned pk2(float a, float b) { f32v2 f = {a, b}; bf16v2 r = __builtin_convertvector(f, bf16v2); return __builtin_bit_cast(unsigned, r); }
; DI float bflo(unsigned w) { return __uint_as_float(w << 16); }
; DI float bfhi(unsigned w) { return __uint_as_float(w & 0xffff0000u); }
; DI void store_gated(const Params& p, int R, int colbase, f32x16 (&o)[4], float mult, const float* wv, int h) {
; #pragma unroll
;   for (int d0 = 0; d0 < 4; ++d0)
; #pragma unroll
;     for (int g = 0; g < 4; ++g) {
;       const int dv = 32 * d0 + 8 * g + 4 * h;
;       const size_t off = (size_t)R * DM + colbase + dv;
;       const u32x2 gg = *(const u32x2*)(p.Gs + off);
;       float v0 = o[d0][4 * g] * mult, v1 = o[d0][4 * g + 1] * mult, v2 = o[d0][4 * g + 2] * mult, v3 = o[d0][4 * g + 3] * mult;
;       if (wv) { v0 *= wv[dv]; v1 *= wv[dv + 1]; v2 *= wv[dv + 2]; v3 *= wv[dv + 3]; }
;       u32x2 ov = {pk2(v0 * bflo(gg[0]), v1 * bfhi(gg[0])), pk2(v2 * bflo(gg[1]), v3 * bfhi(gg[1]))};
;       *(u32x2*)(p.H + off) = ov;
;       __builtin_amdgcn_sched_barrier(0);
;     }
; }
	v_mov_b32_e32 v34, v110
	v_mov_b32_e32 v35, v111
	v_lshlrev_b32_e32 v38, 16, v34
	v_and_b32_e32 v39, 0xffff0000, v34
	v_pk_mul_f32 v[36:37], v[36:37], v[38:39]
	v_lshlrev_b32_e32 v38, 16, v35
	v_cvt_pk_bf16_f32 v34, v36, v37
	v_pk_mul_f32 v[36:37], v[44:45], v[0:1] op_sel_hi:[1,0]
	v_and_b32_e32 v39, 0xffff0000, v35
	v_pk_mul_f32 v[36:37], v[36:37], v[38:39]
	s_nop 0
	v_cvt_pk_bf16_f32 v35, v36, v37
	global_store_dwordx2 v[50:51], v[34:35], off offset:96
	v_pk_mul_f32 v[36:37], v[46:47], v[0:1] op_sel_hi:[1,0]
	v_pk_mul_f32 v[38:39], v[48:49], v[0:1] op_sel_hi:[1,0]
	s_waitcnt vmcnt(15)
	v_mov_b32_e32 v34, v112
	v_mov_b32_e32 v35, v113
	v_lshlrev_b32_e32 v40, 16, v34
	v_and_b32_e32 v41, 0xffff0000, v34
	v_lshlrev_b32_e32 v34, 16, v35
	v_and_b32_e32 v35, 0xffff0000, v35
	v_pk_mul_f32 v[36:37], v[36:37], v[40:41]
	v_pk_mul_f32 v[34:35], v[38:39], v[34:35]
	v_cvt_pk_bf16_f32 v36, v36, v37
	v_cvt_pk_bf16_f32 v37, v34, v35
	global_store_dwordx2 v[50:51], v[36:37], off offset:112
	v_pk_mul_f32 v[18:19], v[18:19], v[0:1] op_sel_hi:[1,0]
	v_pk_mul_f32 v[20:21], v[20:21], v[0:1] op_sel_hi:[1,0]
	s_waitcnt vmcnt(15)
	v_mov_b32_e32 v34, v114
	v_mov_b32_e32 v35, v115
	v_lshlrev_b32_e32 v36, 16, v34
	v_and_b32_e32 v37, 0xffff0000, v34
	v_lshlrev_b32_e32 v34, 16, v35
	v_and_b32_e32 v35, 0xffff0000, v35
	v_pk_mul_f32 v[18:19], v[18:19], v[36:37]
	v_pk_mul_f32 v[20:21], v[20:21], v[34:35]
	v_cvt_pk_bf16_f32 v18, v18, v19
	v_cvt_pk_bf16_f32 v19, v20, v21
	global_store_dwordx2 v[50:51], v[18:19], off offset:128
	v_pk_mul_f32 v[20:21], v[22:23], v[0:1] op_sel_hi:[1,0]
	s_waitcnt vmcnt(15)
	v_mov_b32_e32 v18, v116
	v_mov_b32_e32 v19, v117
	v_lshlrev_b32_e32 v22, 16, v18
	v_and_b32_e32 v23, 0xffff0000, v18
	v_pk_mul_f32 v[20:21], v[20:21], v[22:23]
	v_lshlrev_b32_e32 v22, 16, v19
	v_cvt_pk_bf16_f32 v18, v20, v21
	v_pk_mul_f32 v[20:21], v[24:25], v[0:1] op_sel_hi:[1,0]
	v_and_b32_e32 v23, 0xffff0000, v19
	v_pk_mul_f32 v[20:21], v[20:21], v[22:23]
	s_nop 0
	v_cvt_pk_bf16_f32 v19, v20, v21
	global_store_dwordx2 v[50:51], v[18:19], off offset:144
	v_pk_mul_f32 v[20:21], v[26:27], v[0:1] op_sel_hi:[1,0]
	s_waitcnt vmcnt(15)
	v_mov_b32_e32 v18, v118
	v_mov_b32_e32 v19, v119
	v_lshlrev_b32_e32 v22, 16, v18
	v_and_b32_e32 v23, 0xffff0000, v18
	v_pk_mul_f32 v[20:21], v[20:21], v[22:23]
	v_lshlrev_b32_e32 v22, 16, v19
	v_cvt_pk_bf16_f32 v18, v20, v21
	v_pk_mul_f32 v[20:21], v[28:29], v[0:1] op_sel_hi:[1,0]
	v_and_b32_e32 v23, 0xffff0000, v19
	v_pk_mul_f32 v[20:21], v[20:21], v[22:23]
	s_nop 0
	v_cvt_pk_bf16_f32 v19, v20, v21
	global_store_dwordx2 v[50:51], v[18:19], off offset:160
	v_pk_mul_f32 v[20:21], v[30:31], v[0:1] op_sel_hi:[1,0]
	v_pk_mul_f32 v[22:23], v[32:33], v[0:1] op_sel_hi:[1,0]
	s_waitcnt vmcnt(15)
	v_mov_b32_e32 v18, v120
	v_mov_b32_e32 v19, v121
	v_lshlrev_b32_e32 v24, 16, v18
	v_and_b32_e32 v25, 0xffff0000, v18
	v_lshlrev_b32_e32 v18, 16, v19
	v_and_b32_e32 v19, 0xffff0000, v19
	v_pk_mul_f32 v[20:21], v[20:21], v[24:25]
	v_pk_mul_f32 v[18:19], v[22:23], v[18:19]
	v_cvt_pk_bf16_f32 v20, v20, v21
	v_cvt_pk_bf16_f32 v21, v18, v19
	global_store_dwordx2 v[50:51], v[20:21], off offset:176
	v_pk_mul_f32 v[2:3], v[2:3], v[0:1] op_sel_hi:[1,0]
	v_pk_mul_f32 v[4:5], v[4:5], v[0:1] op_sel_hi:[1,0]
	s_waitcnt vmcnt(15)
	v_mov_b32_e32 v18, v122
	v_mov_b32_e32 v19, v123
	v_lshlrev_b32_e32 v20, 16, v18
	v_and_b32_e32 v21, 0xffff0000, v18
	v_lshlrev_b32_e32 v18, 16, v19
	v_and_b32_e32 v19, 0xffff0000, v19
	v_pk_mul_f32 v[2:3], v[2:3], v[20:21]
	v_pk_mul_f32 v[4:5], v[4:5], v[18:19]
	v_cvt_pk_bf16_f32 v2, v2, v3
	v_cvt_pk_bf16_f32 v3, v4, v5
	global_store_dwordx2 v[50:51], v[2:3], off offset:192
	v_pk_mul_f32 v[4:5], v[6:7], v[0:1] op_sel_hi:[1,0]
	s_waitcnt vmcnt(15)
	v_mov_b32_e32 v2, v124
	v_mov_b32_e32 v3, v125
	v_lshlrev_b32_e32 v6, 16, v2
	v_and_b32_e32 v7, 0xffff0000, v2
	v_pk_mul_f32 v[4:5], v[4:5], v[6:7]
	v_lshlrev_b32_e32 v6, 16, v3
	v_cvt_pk_bf16_f32 v2, v4, v5
	v_pk_mul_f32 v[4:5], v[8:9], v[0:1] op_sel_hi:[1,0]
	v_and_b32_e32 v7, 0xffff0000, v3
	v_pk_mul_f32 v[4:5], v[4:5], v[6:7]
	s_nop 0
	v_cvt_pk_bf16_f32 v3, v4, v5
	global_store_dwordx2 v[50:51], v[2:3], off offset:208
	v_pk_mul_f32 v[4:5], v[10:11], v[0:1] op_sel_hi:[1,0]
	s_waitcnt vmcnt(15)
	v_mov_b32_e32 v2, v126
	v_mov_b32_e32 v3, v127
	v_lshlrev_b32_e32 v6, 16, v2
	v_and_b32_e32 v7, 0xffff0000, v2
	v_pk_mul_f32 v[4:5], v[4:5], v[6:7]
	v_lshlrev_b32_e32 v6, 16, v3
	v_cvt_pk_bf16_f32 v2, v4, v5
	v_pk_mul_f32 v[4:5], v[12:13], v[0:1] op_sel_hi:[1,0]
	v_and_b32_e32 v7, 0xffff0000, v3
	v_pk_mul_f32 v[4:5], v[4:5], v[6:7]
	s_nop 0
	v_cvt_pk_bf16_f32 v3, v4, v5
	global_store_dwordx2 v[50:51], v[2:3], off offset:224
	v_pk_mul_f32 v[4:5], v[14:15], v[0:1] op_sel_hi:[1,0]
	v_pk_mul_f32 v[6:7], v[16:17], v[0:1] op_sel_hi:[1,0]
	s_waitcnt vmcnt(15)
	v_mov_b32_e32 v2, v128
	v_mov_b32_e32 v3, v129
	v_lshlrev_b32_e32 v8, 16, v2
	v_and_b32_e32 v9, 0xffff0000, v2
	v_lshlrev_b32_e32 v2, 16, v3
	v_and_b32_e32 v3, 0xffff0000, v3
	v_pk_mul_f32 v[4:5], v[4:5], v[8:9]
	v_pk_mul_f32 v[2:3], v[6:7], v[2:3]
	v_cvt_pk_bf16_f32 v4, v4, v5
	v_cvt_pk_bf16_f32 v5, v2, v3
	global_store_dwordx2 v[50:51], v[4:5], off offset:240
